# grid barriers: non-last XCD leaders poll the TOP arrival counter itself (released directly by the last leader's add) instead of a second generation counter bumped after that atomic returned
# speedup vs baseline: 1.0033x; 1.0033x over previous
; __device__ __forceinline__ unsigned xb_ld(unsigned* p)              { return __hip_atomic_load(p, __ATOMIC_RELAXED, __HIP_MEMORY_SCOPE_AGENT); }
; __device__ __forceinline__ unsigned xb_add(unsigned* p, unsigned v) { return __hip_atomic_fetch_add(p, v, __ATOMIC_RELAXED, __HIP_MEMORY_SCOPE_AGENT); }
; #define XB_SPIN(cond, bar) do { unsigned _sp = 0; while (cond) { __builtin_amdgcn_s_sleep(1); \
;     if ((++_sp & 255u) == 0u) { if (xb_ld(&(bar)[XB_TMO])) break; if (_sp > XB_SPIN_CAP) { atomicAdd(&(bar)[XB_TMO], 1u); break; } } } } while (0)
; __device__ __forceinline__ void xcd_barrier(const XcdBarrier& b) {
;     ...
;             const unsigned og = xb_add(&bar[XB_TOP], 1u);
;             const unsigned tg = og / nx;
;             if (og + 1u == (tg + 1u) * nx) xb_add(&bar[XB_TOPGEN], 1u);
;             else XB_SPIN(xb_ld(&bar[XB_TOPGEN]) == tg, bar);
.LBB0_166:
	s_or_b64 exec, exec, s[10:11]
	v_cvt_f32_u32_e32 v3, v0
	s_waitcnt vmcnt(0)
	v_readfirstlane_b32 s8, v2
	s_add_u32 s10, s70, 0x2303500
	s_addc_u32 s11, s71, 0
	v_rcp_iflag_f32_e32 v3, v3
	v_add_u32_e32 v1, s8, v1
	v_add_u32_e32 v4, 1, v1
	s_mov_b64 s[12:13], -1
	v_mul_f32_e32 v2, 0x4f7ffffe, v3
	v_cvt_u32_f32_e32 v2, v2
	v_sub_u32_e32 v3, 0, v0
	v_mul_lo_u32 v3, v3, v2
	v_mul_hi_u32 v3, v2, v3
	v_add_u32_e32 v2, v2, v3
	v_mul_hi_u32 v2, v1, v2
	v_mul_lo_u32 v3, v2, v0
	v_sub_u32_e32 v1, v1, v3
	v_add_u32_e32 v5, 1, v2
	v_cmp_ge_u32_e32 vcc, v1, v0
	v_sub_u32_e32 v3, v1, v0
	s_nop 0
	v_cndmask_b32_e32 v2, v2, v5, vcc
	v_cndmask_b32_e32 v1, v1, v3, vcc
	v_add_u32_e32 v3, 1, v2
	v_cmp_ge_u32_e32 vcc, v1, v0
	s_nop 1
	v_cndmask_b32_e32 v2, v2, v3, vcc
	v_mul_lo_u32 v1, v0, v2
	v_add_u32_e32 v0, v1, v0
	v_cmp_ne_u32_e32 vcc, v4, v0
	v_mov_b32_e32 v3, v0
	v_mov_b32_e32 v5, 0x2303000
	v_mov_b64_e32 v[0:1], s[10:11]
	s_and_saveexec_b64 s[8:9], vcc
	s_cbranch_execz .LBB0_178
	v_mov_b32_e32 v0, 0
	global_load_dword v1, v5, s[70:71] offset:1024 sc1
	s_mov_b64 s[20:21], 0
	s_waitcnt vmcnt(0)
	v_cmp_lt_u32_e32 vcc, v1, v3
	s_and_saveexec_b64 s[18:19], vcc
	s_cbranch_execz .LBB0_177
	s_add_u32 s12, s70, 0x2300200
	s_addc_u32 s13, s71, 0
	s_mov_b32 s14, 1
	s_branch .LBB0_170

.LBB0_174:
	global_load_dword v1, v5, s[70:71] offset:1024 sc1
	s_add_i32 s14, s14, 1
	s_mov_b64 s[46:47], -1
	s_waitcnt vmcnt(0)
	v_cmp_ge_u32_e32 vcc, v1, v3
	s_orn2_b64 s[52:53], vcc, exec
	s_branch .LBB0_169

; __device__ __forceinline__ unsigned xb_ld(unsigned* p)              { return __hip_atomic_load(p, __ATOMIC_RELAXED, __HIP_MEMORY_SCOPE_AGENT); }
; __device__ __forceinline__ unsigned xb_add(unsigned* p, unsigned v) { return __hip_atomic_fetch_add(p, v, __ATOMIC_RELAXED, __HIP_MEMORY_SCOPE_AGENT); }
; #define XB_SPIN(cond, bar) do { unsigned _sp = 0; while (cond) { __builtin_amdgcn_s_sleep(1); \
;     if ((++_sp & 255u) == 0u) { if (xb_ld(&(bar)[XB_TMO])) break; if (_sp > XB_SPIN_CAP) { atomicAdd(&(bar)[XB_TMO], 1u); break; } } } } while (0)
; __device__ __forceinline__ void xcd_barrier(const XcdBarrier& b) {
;     ...
;             const unsigned og = xb_add(&bar[XB_TOP], 1u);
;             const unsigned tg = og / nx;
;             if (og + 1u == (tg + 1u) * nx) xb_add(&bar[XB_TOPGEN], 1u);
;             else XB_SPIN(xb_ld(&bar[XB_TOPGEN]) == tg, bar);
.LBB0_259:
	s_or_b64 exec, exec, s[8:9]
	v_cvt_f32_u32_e32 v3, v0
	s_waitcnt vmcnt(0)
	v_readfirstlane_b32 s6, v2
	s_add_u32 s8, s70, 0x2303500
	s_addc_u32 s9, s71, 0
	v_rcp_iflag_f32_e32 v3, v3
	v_add_u32_e32 v1, s6, v1
	v_add_u32_e32 v4, 1, v1
	s_mov_b64 s[10:11], -1
	v_mul_f32_e32 v2, 0x4f7ffffe, v3
	v_cvt_u32_f32_e32 v2, v2
	v_sub_u32_e32 v3, 0, v0
	v_mul_lo_u32 v3, v3, v2
	v_mul_hi_u32 v3, v2, v3
	v_add_u32_e32 v2, v2, v3
	v_mul_hi_u32 v2, v1, v2
	v_mul_lo_u32 v3, v2, v0
	v_sub_u32_e32 v1, v1, v3
	v_add_u32_e32 v5, 1, v2
	v_cmp_ge_u32_e32 vcc, v1, v0
	v_sub_u32_e32 v3, v1, v0
	s_nop 0
	v_cndmask_b32_e32 v2, v2, v5, vcc
	v_cndmask_b32_e32 v1, v1, v3, vcc
	v_add_u32_e32 v3, 1, v2
	v_cmp_ge_u32_e32 vcc, v1, v0
	s_nop 1
	v_cndmask_b32_e32 v2, v2, v3, vcc
	v_mul_lo_u32 v1, v0, v2
	v_add_u32_e32 v0, v1, v0
	v_cmp_ne_u32_e32 vcc, v4, v0
	v_mov_b32_e32 v3, v0
	v_mov_b32_e32 v5, 0x2303000
	v_mov_b64_e32 v[0:1], s[8:9]
	s_and_saveexec_b64 s[6:7], vcc
	s_cbranch_execz .LBB0_271
	v_mov_b32_e32 v0, 0
	global_load_dword v1, v5, s[70:71] offset:1024 sc1
	s_mov_b64 s[18:19], 0
	s_waitcnt vmcnt(0)
	v_cmp_lt_u32_e32 vcc, v1, v3
	s_and_saveexec_b64 s[12:13], vcc
	s_cbranch_execz .LBB0_270
	s_add_u32 s10, s70, 0x2300200
	s_addc_u32 s11, s71, 0
	s_mov_b32 s14, 1
	s_branch .LBB0_263

.LBB0_267:
	global_load_dword v1, v5, s[70:71] offset:1024 sc1
	s_add_i32 s14, s14, 1
	s_mov_b64 s[28:29], -1
	s_waitcnt vmcnt(0)
	v_cmp_ge_u32_e32 vcc, v1, v3
	s_orn2_b64 s[48:49], vcc, exec
	s_branch .LBB0_262

.LBB0_334:
	global_load_dword v1, v5, s[70:71] offset:1024 sc1
	s_add_i32 s14, s14, 1
	s_mov_b64 s[24:25], -1
	s_waitcnt vmcnt(0)
	v_cmp_ge_u32_e32 vcc, v1, v3
	s_orn2_b64 s[28:29], vcc, exec
	s_branch .LBB0_329

; __device__ __forceinline__ unsigned xb_ld(unsigned* p)              { return __hip_atomic_load(p, __ATOMIC_RELAXED, __HIP_MEMORY_SCOPE_AGENT); }
; __device__ __forceinline__ unsigned xb_add(unsigned* p, unsigned v) { return __hip_atomic_fetch_add(p, v, __ATOMIC_RELAXED, __HIP_MEMORY_SCOPE_AGENT); }
; #define XB_SPIN(cond, bar) do { unsigned _sp = 0; while (cond) { __builtin_amdgcn_s_sleep(1); \
;     if ((++_sp & 255u) == 0u) { if (xb_ld(&(bar)[XB_TMO])) break; if (_sp > XB_SPIN_CAP) { atomicAdd(&(bar)[XB_TMO], 1u); break; } } } } while (0)
; __device__ __forceinline__ void xcd_barrier(const XcdBarrier& b) {
;     ...
;             const unsigned og = xb_add(&bar[XB_TOP], 1u);
;             const unsigned tg = og / nx;
;             if (og + 1u == (tg + 1u) * nx) xb_add(&bar[XB_TOPGEN], 1u);
;             else XB_SPIN(xb_ld(&bar[XB_TOPGEN]) == tg, bar);
.LBB0_802:
	s_or_b64 exec, exec, s[10:11]
	v_cvt_f32_u32_e32 v3, v0
	s_waitcnt vmcnt(0)
	v_readfirstlane_b32 s3, v2
	s_add_u32 s10, s70, 0x2303500
	s_addc_u32 s11, s71, 0
	v_rcp_iflag_f32_e32 v3, v3
	v_add_u32_e32 v1, s3, v1
	v_add_u32_e32 v4, 1, v1
	s_mov_b64 s[12:13], -1
	v_mul_f32_e32 v2, 0x4f7ffffe, v3
	v_cvt_u32_f32_e32 v2, v2
	v_sub_u32_e32 v3, 0, v0
	v_mul_lo_u32 v3, v3, v2
	v_mul_hi_u32 v3, v2, v3
	v_add_u32_e32 v2, v2, v3
	v_mul_hi_u32 v2, v1, v2
	v_mul_lo_u32 v3, v2, v0
	v_sub_u32_e32 v1, v1, v3
	v_add_u32_e32 v5, 1, v2
	v_cmp_ge_u32_e32 vcc, v1, v0
	v_sub_u32_e32 v3, v1, v0
	s_nop 0
	v_cndmask_b32_e32 v2, v2, v5, vcc
	v_cndmask_b32_e32 v1, v1, v3, vcc
	v_add_u32_e32 v3, 1, v2
	v_cmp_ge_u32_e32 vcc, v1, v0
	s_nop 1
	v_cndmask_b32_e32 v2, v2, v3, vcc
	v_mul_lo_u32 v1, v0, v2
	v_add_u32_e32 v0, v1, v0
	v_cmp_ne_u32_e32 vcc, v4, v0
	v_mov_b32_e32 v3, v0
	v_mov_b32_e32 v5, 0x2303000
	v_mov_b64_e32 v[0:1], s[10:11]
	s_and_saveexec_b64 s[8:9], vcc
	s_cbranch_execz .LBB0_814
	v_mov_b32_e32 v0, 0
	global_load_dword v1, v5, s[70:71] offset:1024 sc1
	s_mov_b64 s[18:19], 0
	s_waitcnt vmcnt(0)
	v_cmp_lt_u32_e32 vcc, v1, v3
	s_and_saveexec_b64 s[14:15], vcc
	s_cbranch_execz .LBB0_813
	s_add_u32 s12, s70, 0x2300200
	s_addc_u32 s13, s71, 0
	s_mov_b32 s3, 1
	s_branch .LBB0_806

.LBB0_810:
	global_load_dword v1, v5, s[70:71] offset:1024 sc1
	s_add_i32 s3, s3, 1
	s_mov_b64 s[22:23], -1
	s_waitcnt vmcnt(0)
	v_cmp_ge_u32_e32 vcc, v1, v3
	s_orn2_b64 s[26:27], vcc, exec
	s_branch .LBB0_805
